# attention: 4-slot LDS ring, K/V tiles prefetched 2 ahead with vmcnt(4) (tests DMA-latency theory)
# baseline (speedup 1.0000x reference)
; #define AT_ADV() do { kg[0] += 64 * 1024; kg[1] += 64 * 1024; vg[0] += 64; vg[1] += 64; } while (0)
; __device__ __forceinline__ void attn_unit(unsigned char* ws, const float* sub_g, LAS unsigned char* lds, int h, int qb, float negM, float lam) {
;     ...
;     const bf16_t* Qp = (const bf16_t*)(ws + WS_Q); const bf16_t* Kp = (const bf16_t*)(ws + WS_K); const bf16_t* VTp = (const bf16_t*)(ws + WS_VT);
;     bf16x8 qf[4];
;     {
;         const bf16_t* qp = Qp + (size_t)(qrow0 + r32) * 1024 + (h * 2 + map) * 64 + 8 * hi;
; #pragma unroll
;         for (int d0 = 0; d0 < 4; ++d0) qf[d0] = *(const bf16x8*)(qp + 16 * d0);
;     }
;     const bf16_t* kg[2]; const bf16_t* vg[2];
; #pragma unroll
;     for (int i = 0; i < 2; ++i) {
;         const int g = 2 * wid + i;
;         const int kr = 4 * g + (lane >> 4), kc = (lane & 15) ^ (kr & 15);
;         kg[i] = Kp + (size_t)kr * 1024 + h * 128 + kc * 8;
;         const int vr = 8 * g + (lane >> 3), vc = (lane & 7) ^ ((vr >> 1) & 7);
;         vg[i] = VTp + (size_t)(h * 128 + vr) * NTOK + vc * 8;
;     }
;     const unsigned dmaoff = (unsigned)wid * 2048u;
;     ...
;     int kad[4], vad[4];
; #pragma unroll
;     for (int d0 = 0; d0 < 4; ++d0) kad[d0] = r32 * 256 + (((map * 8 + 2 * d0 + hi) ^ (r32 & 15)) << 4);
; #pragma unroll
;     for (int j = 0; j < 4; ++j) vad[j] = AT_KBYTES + r32 * 128 + (((2 * j + hi) ^ ((r32 >> 1) & 7)) << 4);
;     ...
;     f32x16 o[4];
; #pragma unroll
;     for (int b = 0; b < 4; ++b)
; #pragma unroll
;         for (int r = 0; r < 16; ++r) o[b][r] = 0.f;
;     f32x16 negm;
; #pragma unroll
;     for (int r = 0; r < 16; ++r) negm[r] = negM;
;     float l0 = 0.f, l1 = 0.f;
;     AT_DMA(0); AT_ADV();
;     asm volatile("s_waitcnt vmcnt(0)" ::: "memory");
;     __builtin_amdgcn_s_barrier();
;     AT_DMA(AT_BUF); AT_ADV();
;     f32x16 pa, pb;
;     {
;         f32x16 s0 = negm, s1 = negm;
; #pragma unroll
;         for (int d0 = 0; d0 < 4; ++d0) { s0 = __builtin_amdgcn_mfma_f32_32x32x16_bf16(KFR(0, d0, 0), qf[d0], s0, 0, 0, 0); s1 = __builtin_amdgcn_mfma_f32_32x32x16_bf16(KFR(0, d0, 1), qf[d0], s1, 0, 0, 0); }
; #pragma unroll
;         for (int r = 0; r < 16; ++r) { pa[r] = __builtin_amdgcn_exp2f(s0[r]); pb[r] = __builtin_amdgcn_exp2f(s1[r]); }
;     }
;     asm volatile("s_waitcnt vmcnt(0) lgkmcnt(0)" ::: "memory");
;     __builtin_amdgcn_s_barrier();
.LBB0_830:
	v_readfirstlane_b32 s25, v220
	s_bfe_u32 s29, s25, 0x20006
	s_lshl_b32 s8, s20, 4
	s_and_b32 s8, s8, 0xffffff80
	s_lshl_b32 s21, s29, 5
	s_or_b32 s21, s21, s8
	s_lshr_b32 s28, s25, 8
	v_or_b32_e32 v16, s21, v148
	s_lshl_b32 s8, s20, 7
	v_ashrrev_i32_e32 v17, 31, v16
	s_and_b32 s24, s8, 0x380
	s_lshl_b32 s8, s28, 6
	v_lshlrev_b64 v[16:17], 11, v[16:17]
	s_add_i32 s8, s8, s24
	v_lshl_add_u64 v[16:17], s[4:5], 0, v[16:17]
	s_lshl_b32 s8, s8, 1
	v_lshl_add_u64 v[16:17], v[16:17], 0, s[8:9]
	v_lshlrev_b32_e32 v130, 1, v128
	v_lshl_add_u64 v[16:17], v[16:17], 0, v[130:131]
	global_load_dwordx4 v[112:115], v[16:17], off
	global_load_dwordx4 v[116:119], v[16:17], off offset:32
	global_load_dwordx4 v[120:123], v[16:17], off offset:64
	global_load_dwordx4 v[124:127], v[16:17], off offset:96
	s_lshr_b32 s33, s25, 6
	s_lshr_b32 s8, s25, 5
	s_lshl_b32 s30, s24, 1
	s_add_u32 s30, s3, s30
	s_addc_u32 s31, s18, 0
	s_lshl_b32 s34, s33, 3
	v_or_b32_e32 v130, s34, v150
	v_bitop3_b32 v18, s34, v220, v150 bitop3:0x36
	v_lshlrev_b64 v[16:17], 11, v[130:131]
	v_lshlrev_b32_e32 v18, 4, v18
	v_lshl_add_u64 v[16:17], s[30:31], 0, v[16:17]
	v_and_b32_e32 v130, 0xf0, v18
	v_lshl_add_u64 v[56:57], v[16:17], 0, v[130:131]
	v_lshl_or_b32 v16, s33, 4, v151
	v_lshrrev_b32_e32 v17, 1, v151
	v_xor_b32_e32 v20, v17, v220
	v_add_u32_e32 v18, s24, v16
	v_mov_b64_e32 v[16:17], s[6:7]
	v_mad_u64_u32 v[18:19], s[34:35], v18, s19, v[16:17]
	v_lshlrev_b32_e32 v20, 4, v20
	s_or_b32 s8, s8, 1
	v_and_b32_e32 v130, 0x70, v20
	s_lshl_b32 s34, s8, 2
	v_lshl_add_u64 v[58:59], v[18:19], 0, v[130:131]
	v_or_b32_e32 v130, s34, v150
	v_bitop3_b32 v20, s34, v220, v150 bitop3:0x36
	v_lshlrev_b64 v[18:19], 11, v[130:131]
	v_lshlrev_b32_e32 v20, 4, v20
	v_lshl_add_u64 v[18:19], s[30:31], 0, v[18:19]
	v_and_b32_e32 v130, 0xf0, v20
	v_lshl_add_u64 v[60:61], v[18:19], 0, v[130:131]
	v_lshl_or_b32 v18, s8, 3, v151
	v_lshrrev_b32_e32 v19, 1, v18
	v_add_u32_e32 v18, s24, v18
	s_lshl_b32 s8, s33, 11
	v_mad_u64_u32 v[16:17], s[30:31], v18, s19, v[16:17]
	s_add_i32 s8, s8, 0
	v_xor_b32_e32 v19, v19, v220
	s_add_i32 s31, s8, 0x4000
	s_mov_b32 m0, s8
	v_lshlrev_b32_e32 v18, 4, v19
	global_load_lds_dwordx4 v[56:57], off
	s_mov_b32 m0, s31
	v_and_b32_e32 v130, 0x70, v18
	global_load_lds_dwordx4 v[58:59], off
	s_add_i32 m0, s8, 0x400
	v_lshl_add_u64 v[62:63], v[16:17], 0, v[130:131]
	global_load_lds_dwordx4 v[60:61], off
	s_add_i32 m0, s8, 0x4400
	v_lshl_add_u64 v[16:17], v[56:57], 0, s[10:11]
	global_load_lds_dwordx4 v[62:63], off
	s_add_i32 m0, s8, 0x8000
	s_add_i32 s31, s8, 0xc000
	v_lshl_add_u64 v[20:21], v[58:59], 0, s[12:13]
	s_waitcnt vmcnt(0)
	s_barrier
	global_load_lds_dwordx4 v[16:17], off
	s_mov_b32 m0, s31
	v_lshl_add_u64 v[18:19], v[60:61], 0, s[10:11]
	global_load_lds_dwordx4 v[20:21], off
	s_add_i32 m0, s8, 0x8400
	v_lshl_add_u64 v[22:23], v[62:63], 0, s[12:13]
	global_load_lds_dwordx4 v[18:19], off
	s_add_i32 m0, s8, 0xc400
	s_lshl_b32 s30, s28, 3
	global_load_lds_dwordx4 v[22:23], off
	v_bitop3_b32 v24, s30, v153, v149 bitop3:0x36
	v_lshl_add_u32 v198, v24, 4, v154
	ds_read_b128 v[32:35], v198
	ds_read_b128 v[48:51], v198 offset:8192
	s_waitcnt lgkmcnt(0)
	v_mfma_f32_32x32x16_bf16 v[16:31], v[32:35], v[112:115], v[0:15]
	v_or_b32_e32 v64, s30, v149
	v_bitop3_b32 v32, v64, v153, 2 bitop3:0x36
	v_lshlrev_b32_e32 v65, 4, v32
	v_add_u32_e32 v52, v154, v65
	v_add_u32_e32 v200, v65, v152
	s_mov_b32 s30, 0x8000
	v_lshl_add_u64 v[140:141], v[56:57], 0, s[14:15]
	v_mfma_f32_32x32x16_bf16 v[32:47], v[48:51], v[112:115], v[0:15]
	ds_read_b128 v[48:51], v52
	ds_read_b128 v[52:55], v52 offset:8192
	v_lshl_add_u64 v[142:143], v[60:61], 0, s[14:15]
	v_lshl_add_u64 v[144:145], v[58:59], 0, s[16:17]
	v_lshl_add_u64 v[146:147], v[62:63], 0, s[16:17]
	s_mov_b32 s31, 0x18000
	s_add_i32 m0, s8, 0x10000
	s_nop 0
	global_load_lds_dwordx4 v[140:141], off
	s_add_i32 m0, s8, 0x14000
	s_nop 0
	global_load_lds_dwordx4 v[144:145], off
	s_add_i32 m0, s8, 0x10400
	s_nop 0
	global_load_lds_dwordx4 v[142:143], off
	s_add_i32 m0, s8, 0x14400
	s_nop 0
	global_load_lds_dwordx4 v[146:147], off
	v_lshl_add_u64 v[140:141], v[140:141], 0, s[10:11]
	v_lshl_add_u64 v[142:143], v[142:143], 0, s[10:11]
	v_lshl_add_u64 v[144:145], v[144:145], 0, s[12:13]
	v_lshl_add_u64 v[146:147], v[146:147], 0, s[12:13]
	v_mov_b32_e32 v216, 0
	v_mov_b32_e32 v199, 0
	s_waitcnt lgkmcnt(1)
	v_mfma_f32_32x32x16_bf16 v[16:31], v[48:51], v[116:119], v[16:31]
	v_bitop3_b32 v48, v64, v153, 4 bitop3:0x36
	v_lshlrev_b32_e32 v66, 4, v48
	v_add_u32_e32 v201, v66, v152
	s_mov_b32 s36, 0
	s_mov_b32 s33, 1
	v_mov_b32_e32 v56, v131
	v_mov_b32_e32 v57, v131
	s_waitcnt lgkmcnt(0)
	v_mfma_f32_32x32x16_bf16 v[32:47], v[52:55], v[116:119], v[32:47]
	v_add_u32_e32 v52, v154, v66
	ds_read_b128 v[48:51], v52
	ds_read_b128 v[52:55], v52 offset:8192
	v_mov_b32_e32 v58, v131
	v_mov_b32_e32 v59, v131
	v_mov_b32_e32 v60, v131
	v_mov_b32_e32 v61, v131
	v_mov_b32_e32 v62, v131
	s_waitcnt lgkmcnt(1)
	v_mfma_f32_32x32x16_bf16 v[16:31], v[48:51], v[120:123], v[16:31]
	v_bitop3_b32 v48, v64, v153, 6 bitop3:0x36
	v_lshlrev_b32_e32 v64, 4, v48
	v_add_u32_e32 v202, v64, v152
	v_mov_b32_e32 v63, v131
	v_mov_b32_e32 v65, v131
	v_mov_b32_e32 v66, v131
	v_mov_b32_e32 v67, v131
	s_waitcnt lgkmcnt(0)
	v_mfma_f32_32x32x16_bf16 v[32:47], v[52:55], v[120:123], v[32:47]
	v_add_u32_e32 v52, v154, v64
	ds_read_b128 v[48:51], v52
	ds_read_b128 v[52:55], v52 offset:8192
	s_waitcnt vmcnt(4) lgkmcnt(0)
	v_mov_b32_e32 v64, 0
	v_mov_b32_e32 v68, v131
	v_mov_b32_e32 v69, v131
	s_waitcnt lgkmcnt(1)
; #define AT_DMA(B) do { _Pragma("unroll") for (int i_ = 0; i_ < 2; ++i_) { \
;         __builtin_amdgcn_global_load_lds((const unsigned*)kg[i_], (LAS unsigned*)(lds + (B) + dmaoff + i_ * 1024), 16, 0, 0); \
;         __builtin_amdgcn_global_load_lds((const unsigned*)vg[i_], (LAS unsigned*)(lds + (B) + AT_KBYTES + dmaoff + i_ * 1024), 16, 0, 0); } } while (0)
; #define AT_ADV() do { kg[0] += 64 * 1024; kg[1] += 64 * 1024; vg[0] += 64; vg[1] += 64; } while (0)
; __device__ __forceinline__ void attn_unit(unsigned char* ws, const float* sub_g, LAS unsigned char* lds, int h, int qb, float negM, float lam) {
;     ...
;     f32x16 o[4];
; #pragma unroll
;     for (int b = 0; b < 4; ++b)
; #pragma unroll
;         for (int r = 0; r < 16; ++r) o[b][r] = 0.f;
;     f32x16 negm;
; #pragma unroll
;     for (int r = 0; r < 16; ++r) negm[r] = negM;
;     float l0 = 0.f, l1 = 0.f;
;     AT_DMA(0); AT_ADV();
;     asm volatile("s_waitcnt vmcnt(0)" ::: "memory");
;     __builtin_amdgcn_s_barrier();
;     AT_DMA(AT_BUF); AT_ADV();
;     f32x16 pa, pb;
;     {
;         f32x16 s0 = negm, s1 = negm;
; #pragma unroll
;         for (int d0 = 0; d0 < 4; ++d0) { s0 = __builtin_amdgcn_mfma_f32_32x32x16_bf16(KFR(0, d0, 0), qf[d0], s0, 0, 0, 0); s1 = __builtin_amdgcn_mfma_f32_32x32x16_bf16(KFR(0, d0, 1), qf[d0], s1, 0, 0, 0); }
; #pragma unroll
;         for (int r = 0; r < 16; ++r) { pa[r] = __builtin_amdgcn_exp2f(s0[r]); pb[r] = __builtin_amdgcn_exp2f(s1[r]); }
;     }
;     asm volatile("s_waitcnt vmcnt(0) lgkmcnt(0)" ::: "memory");
;     __builtin_amdgcn_s_barrier();
;     int bV = 0, bK = AT_BUF, bW = 2 * AT_BUF;
	v_mfma_f32_32x32x16_bf16 v[16:31], v[48:51], v[124:127], v[16:31]
	v_mov_b32_e32 v48, 0
	v_mov_b32_e32 v49, v131
	v_mov_b32_e32 v50, v131
	v_mov_b32_e32 v51, v131
	v_mov_b32_e32 v70, v131
	v_mov_b32_e32 v71, v131
	v_mov_b32_e32 v72, v131
	s_waitcnt lgkmcnt(0)
	v_mfma_f32_32x32x16_bf16 v[32:47], v[52:55], v[124:127], v[32:47]
	s_nop 2
	v_exp_f32_e32 v217, v16
	v_exp_f32_e32 v219, v17
	v_exp_f32_e32 v218, v18
	v_exp_f32_e32 v222, v19
	v_exp_f32_e32 v211, v20
	v_exp_f32_e32 v215, v21
	v_exp_f32_e32 v209, v22
	s_nop 1
	v_exp_f32_e32 v130, v32
	v_exp_f32_e32 v187, v33
	v_exp_f32_e32 v183, v34
	v_exp_f32_e32 v190, v35
	v_exp_f32_e32 v184, v36
	v_exp_f32_e32 v192, v37
	v_exp_f32_e32 v185, v38
	v_exp_f32_e32 v213, v23
	v_exp_f32_e32 v193, v39
	v_exp_f32_e32 v210, v24
	v_exp_f32_e32 v188, v40
	v_exp_f32_e32 v214, v25
	v_exp_f32_e32 v196, v41
	v_exp_f32_e32 v207, v26
	v_exp_f32_e32 v191, v42
	v_exp_f32_e32 v208, v27
	v_exp_f32_e32 v197, v43
	v_exp_f32_e32 v205, v28
	v_exp_f32_e32 v189, v44
	v_exp_f32_e32 v206, v29
	v_exp_f32_e32 v194, v45
	v_exp_f32_e32 v204, v30
	v_exp_f32_e32 v186, v46
	v_exp_f32_e32 v203, v31
	v_exp_f32_e32 v195, v47
	v_mov_b32_e32 v16, 0
	v_mov_b32_e32 v17, v131
	v_mov_b32_e32 v18, v131
	v_mov_b32_e32 v19, v131
	v_mov_b32_e32 v20, v131
	v_mov_b32_e32 v21, v131
	v_mov_b32_e32 v22, v131
	v_mov_b32_e32 v23, v131
	v_mov_b32_e32 v24, v131
	v_mov_b32_e32 v25, v131
	v_mov_b32_e32 v26, v131
	v_mov_b32_e32 v27, v131
	v_mov_b32_e32 v28, v131
	v_mov_b32_e32 v29, v131
	v_mov_b32_e32 v30, v131
	v_mov_b32_e32 v31, v131
	v_mov_b32_e32 v32, 0
	v_mov_b32_e32 v33, v131
	v_mov_b32_e32 v34, v131
	v_mov_b32_e32 v35, v131
	v_mov_b32_e32 v36, v131
	v_mov_b32_e32 v37, v131
	v_mov_b32_e32 v38, v131
	v_mov_b32_e32 v39, v131
	v_mov_b32_e32 v40, v131
	v_mov_b32_e32 v41, v131
	v_mov_b32_e32 v42, v131
	v_mov_b32_e32 v43, v131
	v_mov_b32_e32 v44, v131
	v_mov_b32_e32 v45, v131
	v_mov_b32_e32 v46, v131
	v_mov_b32_e32 v47, v131
	v_mov_b32_e32 v52, v131
	v_mov_b32_e32 v53, v131
	v_mov_b32_e32 v54, v131
	v_mov_b32_e32 v55, v131
	v_mov_b32_e32 v73, v131
	v_mov_b32_e32 v74, v131
	v_mov_b32_e32 v75, v131
	v_mov_b32_e32 v76, v131
	v_mov_b32_e32 v77, v131
	v_mov_b32_e32 v78, v131
	v_mov_b32_e32 v79, v131
	s_barrier
	s_branch .LBB0_832
; #define AT_ADV() do { kg[0] += 64 * 1024; kg[1] += 64 * 1024; vg[0] += 64; vg[1] += 64; } while (0)
; __device__ __forceinline__ void attn_unit(unsigned char* ws, const float* sub_g, LAS unsigned char* lds, int h, int qb, float negM, float lam) {
;     ...
;     for (int t = 1; t < AT_NT; ++t) {
;         AT_DMA(bW);
;         if (t + 2 < AT_NT) AT_ADV();
;         SB();
;     ...
;         f32x16 s0, s1;
;         bf16x8 F0 = FLOAD(0), F1 = FLOAD(1), F2;
;         SB();
;         F2 = FLOAD(2); s0 = __builtin_amdgcn_mfma_f32_32x32x16_bf16(F0, qf[0], negm, 0, 0, 0); ADD4(pa, 0); pw[0][0] = cvtpk(pa[0], pa[1]); SB();
;         F0 = FLOAD(3); s1 = __builtin_amdgcn_mfma_f32_32x32x16_bf16(F1, qf[0], negm, 0, 0, 0); ADD4(pa, 4); pw[0][1] = cvtpk(pa[2], pa[3]); SB();
;         F1 = FLOAD(4); s0 = __builtin_amdgcn_mfma_f32_32x32x16_bf16(F2, qf[1], s0, 0, 0, 0); ADD4(pa, 8); pw[0][2] = cvtpk(pa[4], pa[5]); SB();
;         F2 = FLOAD(5); s1 = __builtin_amdgcn_mfma_f32_32x32x16_bf16(F0, qf[1], s1, 0, 0, 0); ADD4(pa, 12); pw[0][3] = cvtpk(pa[6], pa[7]); SB();
;         F0 = FLOAD(6); s0 = __builtin_amdgcn_mfma_f32_32x32x16_bf16(F1, qf[2], s0, 0, 0, 0); ADD4(pb, 0); pw[1][0] = cvtpk(pa[8], pa[9]); SB();
;         F1 = FLOAD(7); s1 = __builtin_amdgcn_mfma_f32_32x32x16_bf16(F2, qf[2], s1, 0, 0, 0); ADD4(pb, 4); pw[1][1] = cvtpk(pa[10], pa[11]); SB();
;         F2 = FLOAD(8); s0 = __builtin_amdgcn_mfma_f32_32x32x16_bf16(F0, qf[3], s0, 0, 0, 0); ADD4(pb, 8); pw[1][2] = cvtpk(pa[12], pa[13]); SB();
;         F0 = FLOAD(9); s1 = __builtin_amdgcn_mfma_f32_32x32x16_bf16(F1, qf[3], s1, 0, 0, 0); ADD4(pb, 12); pw[1][3] = cvtpk(pa[14], pa[15]); SB();
;         F1 = FLOAD(10); o[0] = __builtin_amdgcn_mfma_f32_32x32x16_bf16(F2, __builtin_bit_cast(bf16x8, pw[0]), o[0], 0, 0, 0); pw[2][0] = cvtpk(pb[0], pb[1]); EXP2(s0, pa, 0); SB();
;         F2 = FLOAD(11); o[1] = __builtin_amdgcn_mfma_f32_32x32x16_bf16(F0, __builtin_bit_cast(bf16x8, pw[0]), o[1], 0, 0, 0); pw[2][1] = cvtpk(pb[2], pb[3]); EXP2(s0, pa, 2); SB();
;         F0 = FLOAD(12); o[2] = __builtin_amdgcn_mfma_f32_32x32x16_bf16(F1, __builtin_bit_cast(bf16x8, pw[0]), o[2], 0, 0, 0); pw[2][2] = cvtpk(pb[4], pb[5]); EXP2(s0, pa, 4); SB();
;         F1 = FLOAD(13); o[3] = __builtin_amdgcn_mfma_f32_32x32x16_bf16(F2, __builtin_bit_cast(bf16x8, pw[0]), o[3], 0, 0, 0); pw[2][3] = cvtpk(pb[6], pb[7]); EXP2(s0, pa, 6); SB();
.LBB0_831:
	v_add_u32_e32 v84, s30, v198
	ds_read_b128 v[80:83], v84
	ds_read_b128 v[224:227], v84 offset:8192
	s_add_i32 s34, s30, 0
	v_add_u32_e32 v84, s34, v200
	ds_read_b128 v[228:231], v84
	v_add_f32_e32 v85, v216, v217
	v_add_f32_e32 v86, v199, v219
	s_waitcnt lgkmcnt(2)
	v_mfma_f32_32x32x16_bf16 v[96:111], v[80:83], v[112:115], v[0:15]
	v_add_f32_e32 v85, v85, v218
	v_add_f32_e32 v80, v86, v222
	v_cvt_pk_bf16_f32 v232, v217, v219
	ds_read_b128 v[236:239], v84 offset:8192
	v_add_f32_e32 v81, v85, v211
	v_add_f32_e32 v80, v80, v215
	v_cvt_pk_bf16_f32 v233, v218, v222
	v_add_f32_e32 v199, v81, v209
	v_add_f32_e32 v223, v80, v213
	s_waitcnt lgkmcnt(2)
	v_mfma_f32_32x32x16_bf16 v[80:95], v[224:227], v[112:115], v[0:15]
	v_add_u32_e32 v222, s34, v201
	ds_read_b128 v[216:219], v222
	v_add_f32_e32 v199, v199, v210
	v_add_f32_e32 v223, v223, v214
	s_waitcnt lgkmcnt(2)
	v_mfma_f32_32x32x16_bf16 v[96:111], v[228:231], v[116:119], v[96:111]
	v_add_f32_e32 v199, v199, v207
	v_add_f32_e32 v226, v223, v208
	v_cvt_pk_bf16_f32 v234, v211, v215
	ds_read_b128 v[222:225], v222 offset:8192
	v_add_f32_e32 v199, v199, v205
	v_add_f32_e32 v211, v226, v206
	v_cvt_pk_bf16_f32 v235, v209, v213
	v_add_f32_e32 v199, v199, v204
	v_add_f32_e32 v211, v211, v203
	s_waitcnt lgkmcnt(2)
	v_mfma_f32_32x32x16_bf16 v[80:95], v[236:239], v[116:119], v[80:95]
	v_add_u32_e32 v209, s34, v202
	ds_read_b128 v[226:229], v209
	v_add_f32_e32 v199, v199, v130
	v_add_f32_e32 v211, v211, v187
	s_waitcnt lgkmcnt(2)
	v_mfma_f32_32x32x16_bf16 v[96:111], v[216:219], v[120:123], v[96:111]
	v_add_f32_e32 v199, v199, v183
	v_add_f32_e32 v211, v211, v190
	v_cvt_pk_bf16_f32 v236, v210, v214
	ds_read_b128 v[240:243], v209 offset:8192
	v_add_f32_e32 v199, v199, v184
	v_add_f32_e32 v209, v211, v192
	v_cvt_pk_bf16_f32 v237, v207, v208
	v_add_f32_e32 v199, v199, v185
	v_add_f32_e32 v213, v209, v193
	s_waitcnt lgkmcnt(2)
	v_mfma_f32_32x32x16_bf16 v[80:95], v[222:225], v[120:123], v[80:95]
	s_add_i32 s36, s35, 0
	v_add_u32_e32 v214, s36, v178
	ds_read_b128 v[208:211], v214 offset:16384
	v_add_f32_e32 v199, v199, v188
	v_add_f32_e32 v207, v213, v196
	s_waitcnt lgkmcnt(2)
	v_mfma_f32_32x32x16_bf16 v[96:111], v[226:229], v[124:127], v[96:111]
	v_add_f32_e32 v199, v199, v191
	v_add_f32_e32 v207, v207, v197
	v_cvt_pk_bf16_f32 v238, v205, v206
	ds_read_b128 v[224:227], v214 offset:20480
	v_add_f32_e32 v199, v199, v189
	v_add_f32_e32 v205, v207, v194
	v_cvt_pk_bf16_f32 v239, v204, v203
	v_add_f32_e32 v216, v199, v186
	v_add_f32_e32 v199, v205, v195
	s_waitcnt lgkmcnt(2)
	v_mfma_f32_32x32x16_bf16 v[80:95], v[240:243], v[124:127], v[80:95]
	s_waitcnt lgkmcnt(1)
	v_mfma_f32_32x32x16_bf16 v[64:79], v[208:211], v[232:235], v[64:79]
	ds_read_b128 v[204:207], v214 offset:24576
	s_nop 5
	v_exp_f32_e32 v217, v96
	v_exp_f32_e32 v219, v97
	v_cvt_pk_bf16_f32 v228, v130, v187
	s_waitcnt lgkmcnt(1)
	v_mfma_f32_32x32x16_bf16 v[48:63], v[224:227], v[232:235], v[48:63]
	ds_read_b128 v[240:243], v214 offset:28672
	v_exp_f32_e32 v218, v98
	v_exp_f32_e32 v222, v99
	v_cvt_pk_bf16_f32 v229, v183, v190
	s_waitcnt lgkmcnt(1)
	v_mfma_f32_32x32x16_bf16 v[32:47], v[204:207], v[232:235], v[32:47]
	v_add_u32_e32 v130, s36, v179
	ds_read_b128 v[96:99], v130 offset:16384
	v_exp_f32_e32 v211, v100
	v_exp_f32_e32 v215, v101
	v_cvt_pk_bf16_f32 v230, v184, v192
	s_waitcnt lgkmcnt(1)
	v_mfma_f32_32x32x16_bf16 v[16:31], v[240:243], v[232:235], v[16:31]
	ds_read_b128 v[224:227], v130 offset:20480
	v_exp_f32_e32 v209, v102
	v_exp_f32_e32 v213, v103
	v_cvt_pk_bf16_f32 v231, v185, v193
	s_waitcnt lgkmcnt(1)
	v_mfma_f32_32x32x16_bf16 v[64:79], v[96:99], v[236:239], v[64:79]
	ds_read_b128 v[100:103], v130 offset:24576
	v_exp_f32_e32 v210, v104
	v_exp_f32_e32 v214, v105
	v_cvt_pk_bf16_f32 v232, v188, v196
	s_waitcnt lgkmcnt(1)
	v_mfma_f32_32x32x16_bf16 v[48:63], v[224:227], v[236:239], v[48:63]
	ds_read_b128 v[96:99], v130 offset:28672
	v_exp_f32_e32 v207, v106
	v_exp_f32_e32 v208, v107
	v_cvt_pk_bf16_f32 v233, v191, v197
	s_waitcnt lgkmcnt(1)
	v_mfma_f32_32x32x16_bf16 v[32:47], v[100:103], v[236:239], v[32:47]
	v_add_u32_e32 v183, s36, v180
	ds_read_b128 v[104:107], v183 offset:16384
	v_exp_f32_e32 v205, v108
	v_exp_f32_e32 v206, v109
	v_cvt_pk_bf16_f32 v234, v189, v194
	s_waitcnt lgkmcnt(1)
	v_mfma_f32_32x32x16_bf16 v[16:31], v[96:99], v[236:239], v[16:31]
	ds_read_b128 v[100:103], v183 offset:20480
	v_exp_f32_e32 v204, v110
	v_exp_f32_e32 v203, v111
	v_cvt_pk_bf16_f32 v235, v186, v195
	s_waitcnt lgkmcnt(1)
	v_mfma_f32_32x32x16_bf16 v[64:79], v[104:107], v[228:231], v[64:79]
	ds_read_b128 v[96:99], v183 offset:24576
	v_exp_f32_e32 v130, v80
	v_exp_f32_e32 v187, v81
	s_waitcnt lgkmcnt(1)
	v_mfma_f32_32x32x16_bf16 v[48:63], v[100:103], v[228:231], v[48:63]
	ds_read_b128 v[104:107], v183 offset:28672
	v_exp_f32_e32 v183, v82
	v_exp_f32_e32 v190, v83
	s_waitcnt lgkmcnt(1)
	v_mfma_f32_32x32x16_bf16 v[32:47], v[96:99], v[228:231], v[32:47]
	v_add_u32_e32 v100, s36, v181
	ds_read_b128 v[80:83], v100 offset:16384
	v_exp_f32_e32 v184, v84
	v_exp_f32_e32 v192, v85
	s_waitcnt lgkmcnt(1)
	v_mfma_f32_32x32x16_bf16 v[16:31], v[104:107], v[228:231], v[16:31]
	ds_read_b128 v[96:99], v100 offset:20480
	v_exp_f32_e32 v185, v86
	v_exp_f32_e32 v193, v87
	s_waitcnt lgkmcnt(1)
	v_mfma_f32_32x32x16_bf16 v[64:79], v[80:83], v[232:235], v[64:79]
	ds_read_b128 v[84:87], v100 offset:24576
	v_exp_f32_e32 v188, v88
	v_exp_f32_e32 v196, v89
	s_waitcnt lgkmcnt(1)
	v_mfma_f32_32x32x16_bf16 v[48:63], v[96:99], v[232:235], v[48:63]
	ds_read_b128 v[80:83], v100 offset:28672
	v_exp_f32_e32 v191, v90
	v_exp_f32_e32 v197, v91
	s_waitcnt lgkmcnt(1)
	v_mfma_f32_32x32x16_bf16 v[32:47], v[84:87], v[232:235], v[32:47]
	v_exp_f32_e32 v189, v92
	v_exp_f32_e32 v194, v93
	s_waitcnt lgkmcnt(0)
	v_mfma_f32_32x32x16_bf16 v[16:31], v[80:83], v[232:235], v[16:31]
	v_exp_f32_e32 v186, v94
	v_exp_f32_e32 v195, v95
	s_waitcnt vmcnt(4) lgkmcnt(0)
	s_mov_b32 s36, s30
	s_add_i32 s30, s30, 0x8000
	s_and_b32 s30, s30, 0x1ffff
	s_xor_b32 s31, s30, 0x10000
	s_add_i32 s33, s33, 1
	s_cmpk_eq_i32 s33, 0x84
	s_barrier
	s_cbranch_scc1 .LBB0_834
.LBB0_832:
	s_add_i32 s34, s8, s31
	s_mov_b32 m0, s34
	s_add_i32 s35, s34, 0x4000
	global_load_lds_dwordx4 v[140:141], off
	s_mov_b32 m0, s35
	s_mov_b32 s35, s36
	global_load_lds_dwordx4 v[144:145], off
	s_add_i32 m0, s34, 0x400
	s_nop 0
	global_load_lds_dwordx4 v[142:143], off
	s_add_i32 m0, s34, 0x4400
	s_cmpk_lt_u32 s33, 0x81
	global_load_lds_dwordx4 v[146:147], off
	s_cbranch_scc0 .LBB0_831
	v_lshl_add_u64 v[146:147], v[146:147], 0, s[12:13]
	v_lshl_add_u64 v[144:145], v[144:145], 0, s[12:13]
	v_lshl_add_u64 v[142:143], v[142:143], 0, s[10:11]
	v_lshl_add_u64 v[140:141], v[140:141], 0, s[10:11]
	s_branch .LBB0_831
